# S5 output tasks: direction 1's operands staged during direction 0
# speedup vs baseline: 1.0042x; 1.0042x over previous
.Ls5o_dir:
	s_cmp_eq_u32 s56, 1
	s_cbranch_scc1 .Ls5o_d1skip
	s_lshl_b32 s100, s36, 1
	s_add_u32 s100, s100, s56
	s_lshl_b32 s100, s100, 4
	s_add_u32 s100, s100, s99
	s_lshl_b32 s101, s100, 12
	s_add_u32 s101, s101, 0xd1c4000
	s_add_u32 s48, s96, s101
	s_addc_u32 s49, s97, 0
	global_load_dwordx4 v[44:47], v8, s[48:49]
	global_load_dwordx4 v[48:51], v8, s[48:49] offset:512
	global_load_dwordx4 v[52:55], v8, s[48:49] offset:1024
	global_load_dwordx4 v[56:59], v8, s[48:49] offset:1536
	global_load_dwordx4 v[60:63], v8, s[48:49] offset:2048
	global_load_dwordx4 v[64:67], v8, s[48:49] offset:2560
	global_load_dwordx4 v[68:71], v8, s[48:49] offset:3072
	global_load_dwordx4 v[72:75], v8, s[48:49] offset:3584
	s_lshl_b32 s101, s100, 11
	s_add_u32 s101, s101, 0xd1a4000
	s_add_u32 s48, s96, s101
	s_addc_u32 s49, s97, 0
	global_load_dwordx4 v[76:79], v9, s[48:49]
	global_load_dwordx2 v[80:81], v9, s[48:49] offset:16
	v_mov_b32_e32 v82, 0
	v_mov_b32_e32 v83, 0
	s_cmp_eq_u32 s55, 0
	s_cbranch_scc1 .Ls5o_nostatea
	s_sub_u32 s100, s47, 16
	s_lshl_b32 s100, s100, 1
	s_add_u32 s100, s100, s36
	s_lshl_b32 s100, s100, 1
	s_add_u32 s100, s100, s56
	s_lshl_b32 s100, s100, 4
	s_add_u32 s100, s100, s99
	s_lshl_b32 s100, s100, 8
	v_lshl_add_u32 v184, v3, 2, s100
	s_nop 0
	global_load_dword v82, v184, s[74:75]
	global_load_dword v83, v184, s[76:77]
.Ls5o_nostatea:
.Ls5o_d1skip:
	s_sub_u32 s100, s39, 1
	s_sub_u32 s100, s100, s38
	s_add_u32 s101, s54, s39
	s_sub_u32 s101, s101, 1
	s_cmp_eq_u32 s56, 0
	s_cselect_b32 s57, s38, s100
	s_cselect_b32 s100, s54, s101
	s_lshl_b32 s100, s100, 4
	s_add_u32 s100, s100, s99
	s_lshl_b32 s100, s100, 1
	s_add_u32 s100, s100, s56
	s_lshl_b32 s100, s100, 9
	s_add_u32 s100, s100, 0xcba4000
	s_add_u32 s50, s96, s100
	s_addc_u32 s51, s97, 0
	s_cmp_eq_u32 s56, 0
	s_mov_b32 s58, 0xffffc000
	s_mov_b32 s59, -1
	s_cselect_b32 s58, 0x4000, s58
	s_cselect_b32 s59, 0, s59
	s_cmp_le_u32 s57, 0
	s_cbranch_scc1 .Ls5o_ei0
	global_load_dwordx2 v[84:85], v10, s[50:51]
	s_add_u32 s50, s50, s58
	s_addc_u32 s51, s51, s59
	s_cmp_le_u32 s57, 1
	s_cbranch_scc1 .Ls5o_ei0
	global_load_dwordx2 v[86:87], v10, s[50:51]
	s_add_u32 s50, s50, s58
	s_addc_u32 s51, s51, s59
	s_cmp_le_u32 s57, 2
	s_cbranch_scc1 .Ls5o_ei0
	global_load_dwordx2 v[88:89], v10, s[50:51]
	s_add_u32 s50, s50, s58
	s_addc_u32 s51, s51, s59
	s_cmp_le_u32 s57, 3
	s_cbranch_scc1 .Ls5o_ei0
	global_load_dwordx2 v[90:91], v10, s[50:51]
	s_add_u32 s50, s50, s58
	s_addc_u32 s51, s51, s59
	s_cmp_le_u32 s57, 4
	s_cbranch_scc1 .Ls5o_ei0
	global_load_dwordx2 v[92:93], v10, s[50:51]
	s_add_u32 s50, s50, s58
	s_addc_u32 s51, s51, s59
	s_cmp_le_u32 s57, 5
	s_cbranch_scc1 .Ls5o_ei0
	global_load_dwordx2 v[94:95], v10, s[50:51]
	s_add_u32 s50, s50, s58
	s_addc_u32 s51, s51, s59
	s_cmp_le_u32 s57, 6
	s_cbranch_scc1 .Ls5o_ei0
	global_load_dwordx2 v[96:97], v10, s[50:51]
	s_add_u32 s50, s50, s58
	s_addc_u32 s51, s51, s59
	s_cmp_le_u32 s57, 7
	s_cbranch_scc1 .Ls5o_ei0
	global_load_dwordx2 v[98:99], v10, s[50:51]
	s_add_u32 s50, s50, s58
	s_addc_u32 s51, s51, s59
	s_cmp_le_u32 s57, 8
	s_cbranch_scc1 .Ls5o_ei0
	global_load_dwordx2 v[100:101], v10, s[50:51]
	s_add_u32 s50, s50, s58
	s_addc_u32 s51, s51, s59
	s_cmp_le_u32 s57, 9
	s_cbranch_scc1 .Ls5o_ei0
	global_load_dwordx2 v[102:103], v10, s[50:51]
	s_add_u32 s50, s50, s58
	s_addc_u32 s51, s51, s59
	s_cmp_le_u32 s57, 10
	s_cbranch_scc1 .Ls5o_ei0
	global_load_dwordx2 v[104:105], v10, s[50:51]
	s_add_u32 s50, s50, s58
	s_addc_u32 s51, s51, s59
	s_cmp_le_u32 s57, 11
	s_cbranch_scc1 .Ls5o_ei0
	global_load_dwordx2 v[106:107], v10, s[50:51]
	s_add_u32 s50, s50, s58
	s_addc_u32 s51, s51, s59
	s_cmp_le_u32 s57, 12
	s_cbranch_scc1 .Ls5o_ei0
	global_load_dwordx2 v[108:109], v10, s[50:51]
	s_add_u32 s50, s50, s58
	s_addc_u32 s51, s51, s59
	s_cmp_le_u32 s57, 13
	s_cbranch_scc1 .Ls5o_ei0
	global_load_dwordx2 v[110:111], v10, s[50:51]
	s_add_u32 s50, s50, s58
	s_addc_u32 s51, s51, s59
	s_cmp_le_u32 s57, 14
	s_cbranch_scc1 .Ls5o_ei0
	global_load_dwordx2 v[112:113], v10, s[50:51]
	s_add_u32 s50, s50, s58
	s_addc_u32 s51, s51, s59
	s_cmp_le_u32 s57, 15
	s_cbranch_scc1 .Ls5o_ei0
	global_load_dwordx2 v[114:115], v10, s[50:51]
	s_add_u32 s50, s50, s58
	s_addc_u32 s51, s51, s59
.Ls5o_ei0:
	s_waitcnt vmcnt(0)
	s_cmp_lg_u32 s56, 1
	s_cbranch_scc1 .Ls5o_nocopy
	v_mov_b32_e32 v44, v20
	v_mov_b32_e32 v45, v21
	v_mov_b32_e32 v46, v22
	v_mov_b32_e32 v47, v23
	v_mov_b32_e32 v48, v24
	v_mov_b32_e32 v49, v25
	v_mov_b32_e32 v50, v26
	v_mov_b32_e32 v51, v27
	v_mov_b32_e32 v52, v28
	v_mov_b32_e32 v53, v29
	v_mov_b32_e32 v54, v30
	v_mov_b32_e32 v55, v31
	v_mov_b32_e32 v56, v32
	v_mov_b32_e32 v57, v33
	v_mov_b32_e32 v58, v34
	v_mov_b32_e32 v59, v35
	v_mov_b32_e32 v60, v190
	v_mov_b32_e32 v61, v191
	v_mov_b32_e32 v62, v192
	v_mov_b32_e32 v63, v193
	v_mov_b32_e32 v64, v200
	v_mov_b32_e32 v65, v201
	v_mov_b32_e32 v66, v202
	v_mov_b32_e32 v67, v203
	v_mov_b32_e32 v68, v222
	v_mov_b32_e32 v69, v223
	v_mov_b32_e32 v70, v224
	v_mov_b32_e32 v71, v225
	v_mov_b32_e32 v72, v226
	v_mov_b32_e32 v73, v227
	v_mov_b32_e32 v74, v228
	v_mov_b32_e32 v75, v229
	v_mov_b32_e32 v76, v230
	v_mov_b32_e32 v77, v231
	v_mov_b32_e32 v78, v232
	v_mov_b32_e32 v79, v233
	v_mov_b32_e32 v80, v194
	v_mov_b32_e32 v81, v195
	v_mov_b32_e32 v82, v173
	v_mov_b32_e32 v83, v197
.Ls5o_nocopy:
	s_cmp_lg_u32 s56, 0
	s_cbranch_scc1 .Ls5o_packed
	v_cvt_pk_bf16_f32 v36, v20, v21
	v_cvt_pk_bf16_f32 v37, v22, v23
	v_cvt_pk_bf16_f32 v38, v24, v25
	v_cvt_pk_bf16_f32 v39, v26, v27
	v_cvt_pk_bf16_f32 v40, v28, v29
	v_cvt_pk_bf16_f32 v41, v30, v31
	v_cvt_pk_bf16_f32 v42, v32, v33
	v_cvt_pk_bf16_f32 v43, v34, v35
	v_cvt_pk_bf16_f32 v116, v132, -v148
	v_cvt_pk_bf16_f32 v117, v133, -v149
	v_cvt_pk_bf16_f32 v118, v134, -v150
	v_cvt_pk_bf16_f32 v119, v135, -v151
	v_cvt_pk_bf16_f32 v120, v136, -v152
	v_cvt_pk_bf16_f32 v121, v137, -v153
	v_cvt_pk_bf16_f32 v122, v138, -v154
	v_cvt_pk_bf16_f32 v123, v139, -v155
	v_cvt_pk_bf16_f32 v124, v140, -v156
	v_cvt_pk_bf16_f32 v125, v141, -v157
	v_cvt_pk_bf16_f32 v126, v142, -v158
	v_cvt_pk_bf16_f32 v127, v143, -v159
	v_cvt_pk_bf16_f32 v128, v144, -v160
	v_cvt_pk_bf16_f32 v129, v145, -v161
	v_cvt_pk_bf16_f32 v130, v146, -v162
	v_cvt_pk_bf16_f32 v131, v147, -v163
	s_lshl_b32 s100, s36, 1
	s_add_u32 s100, s100, 1
	s_lshl_b32 s100, s100, 4
	s_add_u32 s100, s100, s99
	s_lshl_b32 s101, s100, 12
	s_add_u32 s101, s101, 0xd1c4000
	s_add_u32 s48, s96, s101
	s_addc_u32 s49, s97, 0
	global_load_dwordx4 v[20:23], v8, s[48:49]
	global_load_dwordx4 v[24:27], v8, s[48:49] offset:512
	global_load_dwordx4 v[28:31], v8, s[48:49] offset:1024
	global_load_dwordx4 v[32:35], v8, s[48:49] offset:1536
	global_load_dwordx4 v[190:193], v8, s[48:49] offset:2048
	global_load_dwordx4 v[200:203], v8, s[48:49] offset:2560
	global_load_dwordx4 v[222:225], v8, s[48:49] offset:3072
	global_load_dwordx4 v[226:229], v8, s[48:49] offset:3584
	s_lshl_b32 s101, s100, 11
	s_add_u32 s101, s101, 0xd1a4000
	s_add_u32 s48, s96, s101
	s_addc_u32 s49, s97, 0
	global_load_dwordx4 v[230:233], v9, s[48:49]
	global_load_dwordx2 v[194:195], v9, s[48:49] offset:16
	v_mov_b32_e32 v173, 0
	v_mov_b32_e32 v197, 0
	s_cmp_eq_u32 s55, 0
	s_cbranch_scc1 .Ls5o_nostateb
	s_sub_u32 s100, s47, 16
	s_lshl_b32 s100, s100, 1
	s_add_u32 s100, s100, s36
	s_lshl_b32 s100, s100, 1
	s_add_u32 s100, s100, 1
	s_lshl_b32 s100, s100, 4
	s_add_u32 s100, s100, s99
	s_lshl_b32 s100, s100, 8
	v_lshl_add_u32 v184, v3, 2, s100
	s_nop 0
	global_load_dword v173, v184, s[74:75]
	global_load_dword v197, v184, s[76:77]
.Ls5o_nostateb:
.Ls5o_packed:
	s_nop 1
	v_mfma_f32_16x16x32_bf16 v[132:135], v[36:39], v[44:47], 0
	v_mfma_f32_16x16x32_bf16 v[136:139], v[40:43], v[44:47], 0
	v_mfma_f32_16x16x32_bf16 v[140:143], v[36:39], v[48:51], 0
	v_mfma_f32_16x16x32_bf16 v[144:147], v[40:43], v[48:51], 0
	v_mfma_f32_16x16x32_bf16 v[148:151], v[36:39], v[52:55], 0
	v_mfma_f32_16x16x32_bf16 v[152:155], v[40:43], v[52:55], 0
	v_mfma_f32_16x16x32_bf16 v[156:159], v[36:39], v[56:59], 0
	v_mfma_f32_16x16x32_bf16 v[160:163], v[40:43], v[56:59], 0
	s_nop 7
	ds_write_b32 v6, v132 offset:0
	ds_write_b32 v6, v133 offset:528
	ds_write_b32 v6, v134 offset:1056
	ds_write_b32 v6, v135 offset:1584
	ds_write_b32 v6, v136 offset:8448
	ds_write_b32 v6, v137 offset:8976
	ds_write_b32 v6, v138 offset:9504
	ds_write_b32 v6, v139 offset:10032
	ds_write_b32 v6, v140 offset:64
	ds_write_b32 v6, v141 offset:592
	ds_write_b32 v6, v142 offset:1120
	ds_write_b32 v6, v143 offset:1648
	ds_write_b32 v6, v144 offset:8512
	ds_write_b32 v6, v145 offset:9040
	ds_write_b32 v6, v146 offset:9568
	ds_write_b32 v6, v147 offset:10096
	ds_write_b32 v6, v148 offset:128
	ds_write_b32 v6, v149 offset:656
	ds_write_b32 v6, v150 offset:1184
	ds_write_b32 v6, v151 offset:1712
	ds_write_b32 v6, v152 offset:8576
	ds_write_b32 v6, v153 offset:9104
	ds_write_b32 v6, v154 offset:9632
	ds_write_b32 v6, v155 offset:10160
	ds_write_b32 v6, v156 offset:192
	ds_write_b32 v6, v157 offset:720
	ds_write_b32 v6, v158 offset:1248
	ds_write_b32 v6, v159 offset:1776
	ds_write_b32 v6, v160 offset:8640
	ds_write_b32 v6, v161 offset:9168
	ds_write_b32 v6, v162 offset:9696
	ds_write_b32 v6, v163 offset:10224
	s_nop 1
	v_mfma_f32_16x16x32_bf16 v[132:135], v[36:39], v[60:63], 0
	v_mfma_f32_16x16x32_bf16 v[136:139], v[40:43], v[60:63], 0
	v_mfma_f32_16x16x32_bf16 v[140:143], v[36:39], v[64:67], 0
	v_mfma_f32_16x16x32_bf16 v[144:147], v[40:43], v[64:67], 0
	v_mfma_f32_16x16x32_bf16 v[148:151], v[36:39], v[68:71], 0
	v_mfma_f32_16x16x32_bf16 v[152:155], v[40:43], v[68:71], 0
	v_mfma_f32_16x16x32_bf16 v[156:159], v[36:39], v[72:75], 0
	v_mfma_f32_16x16x32_bf16 v[160:163], v[40:43], v[72:75], 0
	s_nop 7
	ds_write_b32 v6, v132 offset:256
	ds_write_b32 v6, v133 offset:784
	ds_write_b32 v6, v134 offset:1312
	ds_write_b32 v6, v135 offset:1840
	ds_write_b32 v6, v136 offset:8704
	ds_write_b32 v6, v137 offset:9232
	ds_write_b32 v6, v138 offset:9760
	ds_write_b32 v6, v139 offset:10288
	ds_write_b32 v6, v140 offset:320
	ds_write_b32 v6, v141 offset:848
	ds_write_b32 v6, v142 offset:1376
	ds_write_b32 v6, v143 offset:1904
	ds_write_b32 v6, v144 offset:8768
	ds_write_b32 v6, v145 offset:9296
	ds_write_b32 v6, v146 offset:9824
	ds_write_b32 v6, v147 offset:10352
	ds_write_b32 v6, v148 offset:384
	ds_write_b32 v6, v149 offset:912
	ds_write_b32 v6, v150 offset:1440
	ds_write_b32 v6, v151 offset:1968
	ds_write_b32 v6, v152 offset:8832
	ds_write_b32 v6, v153 offset:9360
	ds_write_b32 v6, v154 offset:9888
	ds_write_b32 v6, v155 offset:10416
	ds_write_b32 v6, v156 offset:448
	ds_write_b32 v6, v157 offset:976
	ds_write_b32 v6, v158 offset:1504
	ds_write_b32 v6, v159 offset:2032
	ds_write_b32 v6, v160 offset:8896
	ds_write_b32 v6, v161 offset:9424
	ds_write_b32 v6, v162 offset:9952
	ds_write_b32 v6, v163 offset:10480
	v_mov_b32_e32 v182, v82
	v_mov_b32_e32 v183, v83
	s_cmp_le_u32 s57, 0
	s_cbranch_scc1 .Ls5o_ec1
	v_mul_f32_e32 v184, v81, v183
	v_mul_f32_e32 v185, v81, v182
	v_fma_f32 v0, v80, v182, -v184
	v_fma_f32 v1, v80, v183, v185
	v_add_f32_e32 v182, v0, v84
	v_add_f32_e32 v183, v1, v85
	s_cmp_le_u32 s57, 1
	s_cbranch_scc1 .Ls5o_ec1
	v_mul_f32_e32 v184, v81, v183
	v_mul_f32_e32 v185, v81, v182
	v_fma_f32 v0, v80, v182, -v184
	v_fma_f32 v1, v80, v183, v185
	v_add_f32_e32 v182, v0, v86
	v_add_f32_e32 v183, v1, v87
	s_cmp_le_u32 s57, 2
	s_cbranch_scc1 .Ls5o_ec1
	v_mul_f32_e32 v184, v81, v183
	v_mul_f32_e32 v185, v81, v182
	v_fma_f32 v0, v80, v182, -v184
	v_fma_f32 v1, v80, v183, v185
	v_add_f32_e32 v182, v0, v88
	v_add_f32_e32 v183, v1, v89
	s_cmp_le_u32 s57, 3
	s_cbranch_scc1 .Ls5o_ec1
	v_mul_f32_e32 v184, v81, v183
	v_mul_f32_e32 v185, v81, v182
	v_fma_f32 v0, v80, v182, -v184
	v_fma_f32 v1, v80, v183, v185
	v_add_f32_e32 v182, v0, v90
	v_add_f32_e32 v183, v1, v91
	s_cmp_le_u32 s57, 4
	s_cbranch_scc1 .Ls5o_ec1
	v_mul_f32_e32 v184, v81, v183
	v_mul_f32_e32 v185, v81, v182
	v_fma_f32 v0, v80, v182, -v184
	v_fma_f32 v1, v80, v183, v185
	v_add_f32_e32 v182, v0, v92
	v_add_f32_e32 v183, v1, v93
	s_cmp_le_u32 s57, 5
	s_cbranch_scc1 .Ls5o_ec1
	v_mul_f32_e32 v184, v81, v183
	v_mul_f32_e32 v185, v81, v182
	v_fma_f32 v0, v80, v182, -v184
	v_fma_f32 v1, v80, v183, v185
	v_add_f32_e32 v182, v0, v94
	v_add_f32_e32 v183, v1, v95
	s_cmp_le_u32 s57, 6
	s_cbranch_scc1 .Ls5o_ec1
	v_mul_f32_e32 v184, v81, v183
	v_mul_f32_e32 v185, v81, v182
	v_fma_f32 v0, v80, v182, -v184
	v_fma_f32 v1, v80, v183, v185
	v_add_f32_e32 v182, v0, v96
	v_add_f32_e32 v183, v1, v97
	s_cmp_le_u32 s57, 7
	s_cbranch_scc1 .Ls5o_ec1
	v_mul_f32_e32 v184, v81, v183
	v_mul_f32_e32 v185, v81, v182
	v_fma_f32 v0, v80, v182, -v184
	v_fma_f32 v1, v80, v183, v185
	v_add_f32_e32 v182, v0, v98
	v_add_f32_e32 v183, v1, v99
	s_cmp_le_u32 s57, 8
	s_cbranch_scc1 .Ls5o_ec1
	v_mul_f32_e32 v184, v81, v183
	v_mul_f32_e32 v185, v81, v182
	v_fma_f32 v0, v80, v182, -v184
	v_fma_f32 v1, v80, v183, v185
	v_add_f32_e32 v182, v0, v100
	v_add_f32_e32 v183, v1, v101
	s_cmp_le_u32 s57, 9
	s_cbranch_scc1 .Ls5o_ec1
	v_mul_f32_e32 v184, v81, v183
	v_mul_f32_e32 v185, v81, v182
	v_fma_f32 v0, v80, v182, -v184
	v_fma_f32 v1, v80, v183, v185
	v_add_f32_e32 v182, v0, v102
	v_add_f32_e32 v183, v1, v103
	s_cmp_le_u32 s57, 10
	s_cbranch_scc1 .Ls5o_ec1
	v_mul_f32_e32 v184, v81, v183
	v_mul_f32_e32 v185, v81, v182
	v_fma_f32 v0, v80, v182, -v184
	v_fma_f32 v1, v80, v183, v185
	v_add_f32_e32 v182, v0, v104
	v_add_f32_e32 v183, v1, v105
	s_cmp_le_u32 s57, 11
	s_cbranch_scc1 .Ls5o_ec1
	v_mul_f32_e32 v184, v81, v183
	v_mul_f32_e32 v185, v81, v182
	v_fma_f32 v0, v80, v182, -v184
	v_fma_f32 v1, v80, v183, v185
	v_add_f32_e32 v182, v0, v106
	v_add_f32_e32 v183, v1, v107
	s_cmp_le_u32 s57, 12
	s_cbranch_scc1 .Ls5o_ec1
	v_mul_f32_e32 v184, v81, v183
	v_mul_f32_e32 v185, v81, v182
	v_fma_f32 v0, v80, v182, -v184
	v_fma_f32 v1, v80, v183, v185
	v_add_f32_e32 v182, v0, v108
	v_add_f32_e32 v183, v1, v109
	s_cmp_le_u32 s57, 13
	s_cbranch_scc1 .Ls5o_ec1
	v_mul_f32_e32 v184, v81, v183
	v_mul_f32_e32 v185, v81, v182
	v_fma_f32 v0, v80, v182, -v184
	v_fma_f32 v1, v80, v183, v185
	v_add_f32_e32 v182, v0, v110
	v_add_f32_e32 v183, v1, v111
	s_cmp_le_u32 s57, 14
	s_cbranch_scc1 .Ls5o_ec1
	v_mul_f32_e32 v184, v81, v183
	v_mul_f32_e32 v185, v81, v182
	v_fma_f32 v0, v80, v182, -v184
	v_fma_f32 v1, v80, v183, v185
	v_add_f32_e32 v182, v0, v112
	v_add_f32_e32 v183, v1, v113
	s_cmp_le_u32 s57, 15
	s_cbranch_scc1 .Ls5o_ec1
	v_mul_f32_e32 v184, v81, v183
	v_mul_f32_e32 v185, v81, v182
	v_fma_f32 v0, v80, v182, -v184
	v_fma_f32 v1, v80, v183, v185
	v_add_f32_e32 v182, v0, v114
	v_add_f32_e32 v183, v1, v115
